# attention PV section: packed fp32 adds/fma split into scalar ops, e64 adds re-encoded e32 (bit-identical math)
# baseline (speedup 1.0000x reference)
; #define MFMA(a, b, c) __builtin_amdgcn_mfma_f32_16x16x32_bf16(a, b, c, 0, 0, 0)
; DEV float shfl_l(float v, int srclane) { return __int_as_float(__builtin_amdgcn_ds_bpermute(srclane << 2, __float_as_int(v))); }
; DEV float ex2(float x) { return __builtin_amdgcn_exp2f(x); }
; DEV void attn_item(const Params& p, int layer, int h, int qb, float lam, bf16_t* lds) {
;     ...
;       float ps = 0.f;
; #pragma unroll
;       for (int j = 0; j < 8; j++)
; #pragma unroll
;         for (int r = 0; r < 4; r++) { const float pv = ex2(s[i][j][r] - mnew); s[i][j][r] = pv; ps += pv; }
;       if (i == 0) { mrun0 = mnew; lrun0 = lrun0 * al[0] + ps; } else { mrun1 = mnew; lrun1 = lrun1 * al[1] + ps; }
;     }
;     if (__builtin_amdgcn_ballot_w64(al[0] != 1.f || al[1] != 1.f) != 0ull) {
; #pragma unroll
;       for (int i = 0; i < 2; i++) {
;         float ao[4];
; #pragma unroll
;         for (int r = 0; r < 4; r++) ao[r] = shfl_l(al[i], lg * 4 + r);
; #pragma unroll
;         for (int je = 0; je < 8; je++)
; #pragma unroll
;           for (int r = 0; r < 4; r++) o[i][je][r] *= ao[r];
;       }
;     }
; #pragma unroll
;     for (int ks = 0; ks < 4; ks++) {
;       union { u32x4 u; bf16x8 v; } pf0, pf1;
;       pf0.u[0] = pack2(s[0][2 * ks][0], s[0][2 * ks][1]);
;       pf0.u[1] = pack2(s[0][2 * ks][2], s[0][2 * ks][3]);
;       pf0.u[2] = pack2(s[0][2 * ks + 1][0], s[0][2 * ks + 1][1]);
;       pf0.u[3] = pack2(s[0][2 * ks + 1][2], s[0][2 * ks + 1][3]);
;       pf1.u[0] = pack2(s[1][2 * ks][0], s[1][2 * ks][1]);
;       pf1.u[1] = pack2(s[1][2 * ks][2], s[1][2 * ks][3]);
;       pf1.u[2] = pack2(s[1][2 * ks + 1][0], s[1][2 * ks + 1][1]);
;       pf1.u[3] = pack2(s[1][2 * ks + 1][2], s[1][2 * ks + 1][3]);
; #pragma unroll
;       for (int je = 0; je < 8; je++) {
;         const bf16_t* vp = vq + je * 16 * PS + ks * 32;
;         union { uint2 u[2]; bf16x8 v; } vf;
;         vf.u[0] = *(const uint2*)vp;
;         vf.u[1] = *(const uint2*)(vp + 16);
;         o[0][je] = MFMA(pf0.v, vf.v, o[0][je]);
;         o[1][je] = MFMA(pf1.v, vf.v, o[1][je]);
;       }
;     }
.LBB0_707:
	v_exp_f32_e32 v199, v176
	v_exp_f32_e32 v203, v177
	v_exp_f32_e32 v195, v178
	v_exp_f32_e32 v197, v179
	v_exp_f32_e32 v201, v172
	v_exp_f32_e32 v177, v173
	v_exp_f32_e32 v179, v174
	v_exp_f32_e32 v173, v175
	v_exp_f32_e32 v175, v160
	v_exp_f32_e32 v161, v161
	v_exp_f32_e32 v198, v168
	v_exp_f32_e32 v202, v169
	v_exp_f32_e32 v194, v170
	v_exp_f32_e32 v196, v171
	v_exp_f32_e32 v200, v164
	v_exp_f32_e32 v176, v165
	v_exp_f32_e32 v178, v166
	v_exp_f32_e32 v172, v167
	v_lshl_add_u32 v0, s67, 1, v232
	v_cvt_pk_bf16_f32 v236, v199, v203
	v_cvt_pk_bf16_f32 v237, v195, v197
	v_cvt_pk_bf16_f32 v238, v201, v177
	v_cvt_pk_bf16_f32 v239, v179, v173
	ds_read_b128 v[164:167], v0
	v_cvt_pk_bf16_f32 v240, v198, v202
	v_cvt_pk_bf16_f32 v241, v194, v196
	v_cvt_pk_bf16_f32 v242, v200, v176
	v_cvt_pk_bf16_f32 v243, v178, v172
	ds_read_b128 v[244:247], v0 offset:8704
	ds_read_b128 v[248:251], v0 offset:13056
	s_waitcnt lgkmcnt(2)
	v_mfma_f32_16x16x32_bf16 v[100:103], v[236:239], v[164:167], v[100:103]
	v_exp_f32_e32 v174, v152
	v_mfma_f32_16x16x32_bf16 v[80:83], v[240:243], v[164:167], v[80:83]
	v_exp_f32_e32 v165, v162
	v_exp_f32_e32 v163, v163
	v_exp_f32_e32 v160, v153
	ds_read_b128 v[168:171], v0 offset:4352
	s_waitcnt lgkmcnt(2)
	v_mfma_f32_16x16x32_bf16 v[112:115], v[236:239], v[244:247], v[112:115]
	v_exp_f32_e32 v164, v154
	v_mfma_f32_16x16x32_bf16 v[72:75], v[240:243], v[244:247], v[72:75]
	ds_read_b128 v[244:247], v0 offset:17408
	v_exp_f32_e32 v162, v155
	ds_read_b128 v[152:155], v0 offset:26112
	s_waitcnt lgkmcnt(3)
	v_mfma_f32_16x16x32_bf16 v[92:95], v[236:239], v[248:251], v[92:95]
	v_exp_f32_e32 v167, v156
	v_mfma_f32_16x16x32_bf16 v[68:71], v[240:243], v[248:251], v[68:71]
	ds_read_b128 v[248:251], v0 offset:21760
	v_exp_f32_e32 v157, v157
	s_waitcnt lgkmcnt(3)
	v_mfma_f32_16x16x32_bf16 v[96:99], v[236:239], v[168:171], v[96:99]
	v_exp_f32_e32 v166, v148
	v_mfma_f32_16x16x32_bf16 v[76:79], v[240:243], v[168:171], v[76:79]
	v_exp_f32_e32 v169, v158
	v_exp_f32_e32 v159, v159
	s_waitcnt lgkmcnt(2)
	v_mfma_f32_16x16x32_bf16 v[108:111], v[236:239], v[244:247], v[108:111]
	v_exp_f32_e32 v168, v150
	ds_read_b128 v[208:211], v0 offset:17472
	v_mfma_f32_16x16x32_bf16 v[64:67], v[240:243], v[244:247], v[64:67]
	v_exp_f32_e32 v171, v128
	s_waitcnt lgkmcnt(1)
	v_mfma_f32_16x16x32_bf16 v[244:247], v[240:243], v[248:251], v[60:63]
	v_exp_f32_e32 v221, v129
	v_exp_f32_e32 v156, v149
	v_mfma_f32_16x16x32_bf16 v[104:107], v[236:239], v[152:155], v[104:107]
	ds_read_b128 v[60:63], v0 offset:30464
	v_exp_f32_e32 v170, v120
	v_mfma_f32_16x16x32_bf16 v[152:155], v[240:243], v[152:155], v[56:59]
	v_exp_f32_e32 v220, v121
	v_exp_f32_e32 v158, v151
	v_mfma_f32_16x16x32_bf16 v[88:91], v[236:239], v[248:251], v[88:91]
	ds_read_b128 v[56:59], v0 offset:64
	v_cvt_pk_bf16_f32 v248, v174, v160
	v_cvt_pk_bf16_f32 v249, v164, v162
	s_waitcnt lgkmcnt(1)
	v_mfma_f32_16x16x32_bf16 v[148:151], v[236:239], v[60:63], v[84:87]
	v_cvt_pk_bf16_f32 v236, v175, v161
	v_cvt_pk_bf16_f32 v237, v165, v163
	v_cvt_pk_bf16_f32 v238, v167, v157
	v_cvt_pk_bf16_f32 v239, v169, v159
	v_cvt_pk_bf16_f32 v250, v166, v156
	v_cvt_pk_bf16_f32 v251, v168, v158
	s_waitcnt lgkmcnt(0)
	v_mfma_f32_16x16x32_bf16 v[100:103], v[236:239], v[56:59], v[100:103]
	ds_read_b128 v[84:87], v0 offset:8768
	v_mfma_f32_16x16x32_bf16 v[80:83], v[248:251], v[56:59], v[80:83]
	ds_read_b128 v[56:59], v0 offset:4416
	v_mfma_f32_16x16x32_bf16 v[240:243], v[240:243], v[60:63], v[52:55]
	v_exp_f32_e32 v60, v133
	s_nop 1
	v_exp_f32_e32 v53, v144
	v_exp_f32_e32 v55, v145
	s_waitcnt lgkmcnt(0)
	v_mfma_f32_16x16x32_bf16 v[96:99], v[236:239], v[56:59], v[96:99]
	v_exp_f32_e32 v54, v137
	v_mfma_f32_16x16x32_bf16 v[76:79], v[248:251], v[56:59], v[76:79]
	v_exp_f32_e32 v57, v146
	v_mov_b32_e32 v52, v147
	ds_read_b128 v[144:147], v0 offset:13120
	v_exp_f32_e32 v63, v52
	v_exp_f32_e32 v59, v140
	v_exp_f32_e32 v61, v141
	v_mfma_f32_16x16x32_bf16 v[112:115], v[236:239], v[84:87], v[112:115]
	v_mov_b32_e32 v56, v138
	v_exp_f32_e32 v62, v139
	v_mfma_f32_16x16x32_bf16 v[72:75], v[248:251], v[84:87], v[72:75]
	v_exp_f32_e32 v85, v142
	v_exp_f32_e32 v87, v143
	s_waitcnt lgkmcnt(0)
	v_mfma_f32_16x16x32_bf16 v[92:95], v[236:239], v[144:147], v[92:95]
	v_mov_b32_e32 v52, v136
	ds_read_b128 v[140:143], v0 offset:21824
	ds_read_b128 v[136:139], v0 offset:26176
	v_mfma_f32_16x16x32_bf16 v[68:71], v[248:251], v[144:147], v[68:71]
	ds_read_b128 v[144:147], v0 offset:30528
	v_exp_f32_e32 v52, v52
	v_exp_f32_e32 v56, v56
	v_exp_f32_e32 v58, v132
	v_exp_f32_e32 v84, v134
	v_exp_f32_e32 v86, v135
	v_mfma_f32_16x16x32_bf16 v[108:111], v[236:239], v[208:211], v[108:111]
	v_mfma_f32_16x16x32_bf16 v[64:67], v[248:251], v[208:211], v[64:67]
	v_cvt_pk_bf16_f32 v208, v52, v54
	v_cvt_pk_bf16_f32 v209, v56, v62
	v_cvt_pk_bf16_f32 v210, v58, v60
	s_waitcnt lgkmcnt(2)
	v_mfma_f32_16x16x32_bf16 v[88:91], v[236:239], v[140:143], v[88:91]
	v_cvt_pk_bf16_f32 v211, v84, v86
	s_waitcnt lgkmcnt(1)
	v_mfma_f32_16x16x32_bf16 v[104:107], v[236:239], v[136:139], v[104:107]
	s_waitcnt lgkmcnt(0)
	v_mfma_f32_16x16x32_bf16 v[132:135], v[236:239], v[144:147], v[148:151]
	ds_read_b128 v[236:239], v0 offset:8832
	s_nop 1
	v_cvt_pk_bf16_f32 v148, v53, v55
	v_cvt_pk_bf16_f32 v149, v57, v63
	v_cvt_pk_bf16_f32 v150, v59, v61
	v_cvt_pk_bf16_f32 v151, v85, v87
	v_mfma_f32_16x16x32_bf16 v[144:147], v[248:251], v[144:147], v[240:243]
	s_nop 2
	v_exp_f32_e32 v241, v130
	v_exp_f32_e32 v243, v131
	ds_read_b128 v[128:131], v0 offset:13184
	s_waitcnt lgkmcnt(1)
; #define MFMA(a, b, c) __builtin_amdgcn_mfma_f32_16x16x32_bf16(a, b, c, 0, 0, 0)
; DEV float shfl_l(float v, int srclane) { return __int_as_float(__builtin_amdgcn_ds_bpermute(srclane << 2, __float_as_int(v))); }
; DEV float ex2(float x) { return __builtin_amdgcn_exp2f(x); }
; DEV void attn_item(const Params& p, int layer, int h, int qb, float lam, bf16_t* lds) {
;     ...
;       float ps = 0.f;
; #pragma unroll
;       for (int j = 0; j < 8; j++)
; #pragma unroll
;         for (int r = 0; r < 4; r++) { const float pv = ex2(s[i][j][r] - mnew); s[i][j][r] = pv; ps += pv; }
;       if (i == 0) { mrun0 = mnew; lrun0 = lrun0 * al[0] + ps; } else { mrun1 = mnew; lrun1 = lrun1 * al[1] + ps; }
;     }
;     if (__builtin_amdgcn_ballot_w64(al[0] != 1.f || al[1] != 1.f) != 0ull) {
; #pragma unroll
;       for (int i = 0; i < 2; i++) {
;         float ao[4];
; #pragma unroll
;         for (int r = 0; r < 4; r++) ao[r] = shfl_l(al[i], lg * 4 + r);
; #pragma unroll
;         for (int je = 0; je < 8; je++)
; #pragma unroll
;           for (int r = 0; r < 4; r++) o[i][je][r] *= ao[r];
;       }
;     }
; #pragma unroll
;     for (int ks = 0; ks < 4; ks++) {
;       union { u32x4 u; bf16x8 v; } pf0, pf1;
;       pf0.u[0] = pack2(s[0][2 * ks][0], s[0][2 * ks][1]);
;       pf0.u[1] = pack2(s[0][2 * ks][2], s[0][2 * ks][3]);
;       pf0.u[2] = pack2(s[0][2 * ks + 1][0], s[0][2 * ks + 1][1]);
;       pf0.u[3] = pack2(s[0][2 * ks + 1][2], s[0][2 * ks + 1][3]);
;       pf1.u[0] = pack2(s[1][2 * ks][0], s[1][2 * ks][1]);
;       pf1.u[1] = pack2(s[1][2 * ks][2], s[1][2 * ks][3]);
;       pf1.u[2] = pack2(s[1][2 * ks + 1][0], s[1][2 * ks + 1][1]);
;       pf1.u[3] = pack2(s[1][2 * ks + 1][2], s[1][2 * ks + 1][3]);
; #pragma unroll
;       for (int je = 0; je < 8; je++) {
;         const bf16_t* vp = vq + je * 16 * PS + ks * 32;
;         union { uint2 u[2]; bf16x8 v; } vf;
;         vf.u[0] = *(const uint2*)vp;
;         vf.u[1] = *(const uint2*)(vp + 16);
;         o[0][je] = MFMA(pf0.v, vf.v, o[0][je]);
;         o[1][je] = MFMA(pf1.v, vf.v, o[1][je]);
;       }
;     }
;     __builtin_amdgcn_sched_barrier(0);
;     __syncthreads();
;   }
	v_mfma_f32_16x16x32_bf16 v[112:115], v[148:151], v[236:239], v[112:115]
	v_exp_f32_e32 v240, v122
	v_exp_f32_e32 v242, v123
	v_mfma_f32_16x16x32_bf16 v[72:75], v[208:211], v[236:239], v[72:75]
	v_exp_f32_e32 v237, v124
	v_exp_f32_e32 v239, v125
	v_exp_f32_e32 v236, v116
	v_mfma_f32_16x16x32_bf16 v[140:143], v[248:251], v[140:143], v[244:247]
	v_exp_f32_e32 v238, v117
	ds_read_b128 v[120:123], v0 offset:26240
	v_mfma_f32_16x16x32_bf16 v[136:139], v[248:251], v[136:139], v[152:155]
	v_exp_f32_e32 v245, v126
	v_exp_f32_e32 v247, v127
	ds_read_b128 v[152:155], v0 offset:128
	s_waitcnt lgkmcnt(2)
	v_mfma_f32_16x16x32_bf16 v[92:95], v[148:151], v[128:131], v[92:95]
	ds_read_b128 v[124:127], v0 offset:21888
	v_exp_f32_e32 v244, v118
	v_mfma_f32_16x16x32_bf16 v[68:71], v[208:211], v[128:131], v[68:71]
	ds_read_b128 v[128:131], v0 offset:30592
	v_exp_f32_e32 v246, v119
	s_waitcnt lgkmcnt(2)
	v_mfma_f32_16x16x32_bf16 v[100:103], v[148:151], v[152:155], v[100:103]
	v_mfma_f32_16x16x32_bf16 v[80:83], v[208:211], v[152:155], v[80:83]
	ds_read_b128 v[152:155], v0 offset:4480
	s_waitcnt lgkmcnt(2)
	v_mfma_f32_16x16x32_bf16 v[88:91], v[148:151], v[124:127], v[88:91]
	v_mfma_f32_16x16x32_bf16 v[124:127], v[208:211], v[124:127], v[140:143]
	v_mfma_f32_16x16x32_bf16 v[104:107], v[148:151], v[120:123], v[104:107]
	s_nop 1
	v_cvt_pk_bf16_f32 v140, v170, v220
	v_cvt_pk_bf16_f32 v141, v240, v242
	v_cvt_pk_bf16_f32 v142, v236, v238
	v_mfma_f32_16x16x32_bf16 v[120:123], v[208:211], v[120:123], v[136:139]
	v_cvt_pk_bf16_f32 v143, v244, v246
	s_waitcnt lgkmcnt(1)
	v_mfma_f32_16x16x32_bf16 v[116:119], v[148:151], v[128:131], v[132:135]
	ds_read_b128 v[136:139], v0 offset:192
	s_nop 1
	v_cvt_pk_bf16_f32 v132, v171, v221
	v_cvt_pk_bf16_f32 v133, v241, v243
	v_cvt_pk_bf16_f32 v134, v237, v239
	v_cvt_pk_bf16_f32 v135, v245, v247
	s_waitcnt lgkmcnt(1)
	v_mfma_f32_16x16x32_bf16 v[96:99], v[148:151], v[152:155], v[96:99]
	v_mfma_f32_16x16x32_bf16 v[76:79], v[208:211], v[152:155], v[76:79]
	ds_read_b128 v[152:155], v0 offset:17536
	s_waitcnt lgkmcnt(1)
	v_mfma_f32_16x16x32_bf16 v[100:103], v[132:135], v[136:139], v[100:103]
	v_mfma_f32_16x16x32_bf16 v[80:83], v[140:143], v[136:139], v[80:83]
	ds_read_b128 v[136:139], v0 offset:4544
	v_mfma_f32_16x16x32_bf16 v[128:131], v[208:211], v[128:131], v[144:147]
	s_nop 2
	v_add_f32_e32 v144, 0, v198
	v_add_f32_e32 v145, 0, v199
	s_waitcnt lgkmcnt(1)
	v_mfma_f32_16x16x32_bf16 v[108:111], v[148:151], v[152:155], v[108:111]
	v_add_f32_e32 v148, v202, v144
	v_add_f32_e32 v149, v203, v145
	ds_read_b128 v[144:147], v0 offset:8896
	s_waitcnt lgkmcnt(1)
	v_mfma_f32_16x16x32_bf16 v[96:99], v[132:135], v[136:139], v[96:99]
	v_mfma_f32_16x16x32_bf16 v[76:79], v[140:143], v[136:139], v[76:79]
	v_add_f32_e32 v136, v194, v148
	v_add_f32_e32 v137, v195, v149
	v_add_f32_e32 v136, v196, v136
	v_add_f32_e32 v137, v197, v137
	s_waitcnt lgkmcnt(0)
	v_mfma_f32_16x16x32_bf16 v[112:115], v[132:135], v[144:147], v[112:115]
	v_add_f32_e32 v136, v200, v136
	v_add_f32_e32 v137, v201, v137
	v_add_f32_e32 v136, v176, v136
	v_add_f32_e32 v137, v177, v137
	v_mfma_f32_16x16x32_bf16 v[72:75], v[140:143], v[144:147], v[72:75]
	v_add_f32_e32 v148, v178, v136
	v_add_f32_e32 v149, v179, v137
	ds_read_b128 v[136:139], v0 offset:13248
	v_add_f32_e32 v144, v172, v148
	v_add_f32_e32 v145, v173, v149
	s_waitcnt lgkmcnt(0)
	v_mfma_f32_16x16x32_bf16 v[92:95], v[132:135], v[136:139], v[92:95]
	v_add_f32_e32 v144, v174, v144
	v_add_f32_e32 v145, v175, v145
	v_add_f32_e32 v144, v160, v144
	v_add_f32_e32 v145, v161, v145
	v_mfma_f32_16x16x32_bf16 v[68:71], v[140:143], v[136:139], v[68:71]
	v_add_f32_e32 v144, v164, v144
	v_add_f32_e32 v145, v165, v145
	v_add_f32_e32 v148, v162, v144
	v_add_f32_e32 v149, v163, v145
	ds_read_b128 v[144:147], v0 offset:17600
	v_add_f32_e32 v136, v166, v148
	v_add_f32_e32 v137, v167, v149
	v_mfma_f32_16x16x32_bf16 v[64:67], v[208:211], v[152:155], v[64:67]
	v_add_f32_e32 v136, v156, v136
	v_add_f32_e32 v137, v157, v137
	v_add_f32_e32 v136, v168, v136
	v_add_f32_e32 v137, v169, v137
	s_waitcnt lgkmcnt(0)
	v_mfma_f32_16x16x32_bf16 v[108:111], v[132:135], v[144:147], v[108:111]
	v_add_f32_e32 v136, v158, v136
	v_add_f32_e32 v137, v159, v137
	v_add_f32_e32 v52, v52, v136
	v_add_f32_e32 v53, v53, v137
	ds_read_b128 v[136:139], v0 offset:21952
	v_add_f32_e32 v52, v54, v52
	v_add_f32_e32 v53, v55, v53
	v_mfma_f32_16x16x32_bf16 v[64:67], v[140:143], v[144:147], v[64:67]
	v_add_f32_e32 v52, v56, v52
	v_add_f32_e32 v53, v57, v53
	v_add_f32_e32 v52, v62, v52
	v_add_f32_e32 v53, v63, v53
	s_waitcnt lgkmcnt(0)
	v_mfma_f32_16x16x32_bf16 v[88:91], v[132:135], v[136:139], v[88:91]
	v_add_f32_e32 v52, v58, v52
	v_add_f32_e32 v53, v59, v53
	v_add_f32_e32 v56, v60, v52
	v_add_f32_e32 v57, v61, v53
	ds_read_b128 v[52:55], v0 offset:26304
	v_add_f32_e32 v56, v84, v56
	v_add_f32_e32 v57, v85, v57
	v_mfma_f32_16x16x32_bf16 v[60:63], v[140:143], v[136:139], v[124:127]
	v_add_f32_e32 v56, v86, v56
	v_add_f32_e32 v57, v87, v57
	v_add_f32_e32 v56, v170, v56
	v_add_f32_e32 v57, v171, v57
	s_waitcnt lgkmcnt(0)
	v_mfma_f32_16x16x32_bf16 v[104:107], v[132:135], v[52:55], v[104:107]
	v_add_f32_e32 v56, v220, v56
	v_add_f32_e32 v57, v221, v57
	ds_read_b128 v[124:127], v0 offset:30656
	v_add_f32_e32 v84, v240, v56
	v_add_f32_e32 v85, v241, v57
	v_mfma_f32_16x16x32_bf16 v[56:59], v[140:143], v[52:55], v[120:123]
	v_add_f32_e32 v52, v242, v84
	v_add_f32_e32 v53, v243, v85
	v_add_f32_e32 v52, v236, v52
	v_add_f32_e32 v53, v237, v53
	s_waitcnt lgkmcnt(0)
	v_mfma_f32_16x16x32_bf16 v[84:87], v[132:135], v[124:127], v[116:119]
	v_add_f32_e32 v52, v238, v52
	v_add_f32_e32 v53, v239, v53
	v_add_f32_e32 v52, v244, v52
	v_add_f32_e32 v53, v245, v53
	s_nop 0
	v_add_f32_e32 v52, v246, v52
	v_add_f32_e32 v53, v247, v53
	s_nop 0
	v_fma_f32 v190, v190, v2, v52
	v_fma_f32 v191, v191, v3, v53
	v_mfma_f32_16x16x32_bf16 v[52:55], v[140:143], v[124:127], v[128:131]
	s_add_i32 s77, s77, 1
	s_cmp_eq_u32 s82, s77
	v_add_u32_e32 v234, 0x80, v234
	s_barrier
	s_cbranch_scc1 .LBB0_712
